# residual (EpiRes) epilogues: all 32 h loads pipelined 12 deep with no stores in between, the 32 write-through stores issued together at the end (on top of v33)
# speedup vs baseline: 1.0006x; 1.0006x over previous
.LBB0_1025:
	s_sub_i32 s0, s13, 64
	s_ashr_i32 s1, s13, 31
	s_cmp_lt_i32 s13, 64
	s_cselect_b32 s1, s1, 0
	s_cselect_b32 s0, s13, s0
	s_movk_i32 s5, 0x4800
	s_cselect_b32 s2, s79, s97
	s_cselect_b32 s3, s78, s96
	s_cselect_b32 s5, 0x2400, s5
	s_lshl_b64 s[0:1], s[0:1], 20
	s_add_u32 s0, s3, s0
	s_addc_u32 s1, s2, s1
	s_cmp_gt_i32 s13, 31
	s_cselect_b32 s2, s5, 0
	s_lshl_b32 s2, s2, 2
	v_readlane_b32 s3, v254, 45
	v_lshl_or_b32 v152, s12, 8, v157
	s_add_u32 s2, s3, s2
	v_readlane_b32 s3, v254, 47
	v_ashrrev_i32_e32 v153, 31, v152
	s_addc_u32 s3, s3, 0
	v_lshlrev_b64 v[152:153], 2, v[152:153]
	v_add_u32_e32 v154, 0x5000, v152
	global_load_dwordx4 v[160:163], v154, s[2:3]
	global_load_dwordx4 v[164:167], v154, s[2:3] offset:64
	global_load_dwordx4 v[168:171], v154, s[2:3] offset:512
	global_load_dwordx4 v[172:175], v154, s[2:3] offset:576
	v_add_u32_e32 v159, v152, v132
	v_add_u32_e32 v153, v152, v136
	v_add_u32_e32 v196, v152, v138
	v_add_u32_e32 v197, v152, v140
	v_add_u32_e32 v234, v152, v134
	v_add_u32_e32 v235, v152, v142
	v_add_u32_e32 v210, v152, v144
	v_add_u32_e32 v211, v152, v146
	global_load_dwordx4 v[176:179], v159, s[0:1]
	global_load_dwordx4 v[180:183], v153, s[0:1]
	global_load_dwordx4 v[184:187], v196, s[0:1]
	global_load_dwordx4 v[188:191], v197, s[0:1]
	global_load_dwordx4 v[192:195], v234, s[0:1]
	global_load_dwordx4 v[214:217], v235, s[0:1]
	global_load_dwordx4 v[218:221], v210, s[0:1]
	global_load_dwordx4 v[222:225], v211, s[0:1]
	global_load_dwordx4 v[226:229], v159, s[0:1] offset:64
	global_load_dwordx4 v[230:233], v153, s[0:1] offset:64
	global_load_dwordx4 v[240:243], v196, s[0:1] offset:64
	global_load_dwordx4 v[244:247], v197, s[0:1] offset:64
	v_readlane_b32 s18, v249, 56
	s_mov_b64 s[2:3], -1
	s_andn2_b64 vcc, exec, s[38:39]
	v_readlane_b32 s19, v249, 57
	s_waitcnt vmcnt(11)
	v_pk_fma_f32 v[128:129], v[128:129], v[162:163], v[178:179]
	v_pk_fma_f32 v[126:127], v[126:127], v[160:161], v[176:177]
	global_load_dwordx4 v[176:179], v234, s[0:1] offset:64
	s_waitcnt vmcnt(11)
	v_pk_fma_f32 v[124:125], v[124:125], v[162:163], v[182:183]
	v_pk_fma_f32 v[122:123], v[122:123], v[160:161], v[180:181]
	global_load_dwordx4 v[180:183], v235, s[0:1] offset:64
	s_waitcnt vmcnt(11)
	v_pk_fma_f32 v[120:121], v[120:121], v[162:163], v[186:187]
	v_pk_fma_f32 v[118:119], v[118:119], v[160:161], v[184:185]
	global_load_dwordx4 v[184:187], v210, s[0:1] offset:64
	s_waitcnt vmcnt(11)
	v_pk_fma_f32 v[116:117], v[116:117], v[162:163], v[190:191]
	v_pk_fma_f32 v[114:115], v[114:115], v[160:161], v[188:189]
	global_load_dwordx4 v[188:191], v211, s[0:1] offset:64
	s_waitcnt vmcnt(11)
	v_pk_fma_f32 v[112:113], v[112:113], v[162:163], v[194:195]
	v_pk_fma_f32 v[110:111], v[110:111], v[160:161], v[192:193]
	global_load_dwordx4 v[192:195], v159, s[0:1] offset:512
	s_waitcnt vmcnt(11)
	v_pk_fma_f32 v[108:109], v[108:109], v[162:163], v[216:217]
	v_pk_fma_f32 v[106:107], v[106:107], v[160:161], v[214:215]
	global_load_dwordx4 v[214:217], v153, s[0:1] offset:512
	s_waitcnt vmcnt(11)
	v_pk_fma_f32 v[100:101], v[100:101], v[162:163], v[220:221]
	v_pk_fma_f32 v[98:99], v[98:99], v[160:161], v[218:219]
	global_load_dwordx4 v[218:221], v196, s[0:1] offset:512
	s_waitcnt vmcnt(11)
	v_pk_fma_f32 v[96:97], v[96:97], v[162:163], v[224:225]
	v_pk_fma_f32 v[94:95], v[94:95], v[160:161], v[222:223]
	global_load_dwordx4 v[222:225], v197, s[0:1] offset:512
	s_waitcnt vmcnt(11)
	v_pk_fma_f32 v[104:105], v[104:105], v[166:167], v[228:229]
	v_pk_fma_f32 v[102:103], v[102:103], v[164:165], v[226:227]
	global_load_dwordx4 v[226:229], v234, s[0:1] offset:512
	s_waitcnt vmcnt(11)
	v_pk_fma_f32 v[92:93], v[92:93], v[166:167], v[232:233]
	v_pk_fma_f32 v[90:91], v[90:91], v[164:165], v[230:231]
	global_load_dwordx4 v[230:233], v235, s[0:1] offset:512
	s_waitcnt vmcnt(11)
	v_pk_fma_f32 v[88:89], v[88:89], v[166:167], v[242:243]
	v_pk_fma_f32 v[86:87], v[86:87], v[164:165], v[240:241]
	global_load_dwordx4 v[240:243], v210, s[0:1] offset:512
	s_waitcnt vmcnt(11)
	v_pk_fma_f32 v[84:85], v[84:85], v[166:167], v[246:247]
	v_pk_fma_f32 v[82:83], v[82:83], v[164:165], v[244:245]
	global_load_dwordx4 v[244:247], v211, s[0:1] offset:512
	s_waitcnt vmcnt(11)
	v_pk_fma_f32 v[80:81], v[80:81], v[166:167], v[178:179]
	v_pk_fma_f32 v[78:79], v[78:79], v[164:165], v[176:177]
	global_load_dwordx4 v[176:179], v159, s[0:1] offset:576
	s_waitcnt vmcnt(11)
	v_pk_fma_f32 v[76:77], v[76:77], v[166:167], v[182:183]
	v_pk_fma_f32 v[74:75], v[74:75], v[164:165], v[180:181]
	global_load_dwordx4 v[180:183], v153, s[0:1] offset:576
	s_waitcnt vmcnt(11)
	v_pk_fma_f32 v[72:73], v[72:73], v[166:167], v[186:187]
	v_pk_fma_f32 v[70:71], v[70:71], v[164:165], v[184:185]
	global_load_dwordx4 v[184:187], v196, s[0:1] offset:576
	s_waitcnt vmcnt(11)
	v_pk_fma_f32 v[68:69], v[68:69], v[166:167], v[190:191]
	v_pk_fma_f32 v[66:67], v[66:67], v[164:165], v[188:189]
	global_load_dwordx4 v[188:191], v197, s[0:1] offset:576
	s_waitcnt vmcnt(11)
	v_pk_fma_f32 v[64:65], v[64:65], v[170:171], v[194:195]
	v_pk_fma_f32 v[62:63], v[62:63], v[168:169], v[192:193]
	global_load_dwordx4 v[192:195], v234, s[0:1] offset:576
	s_waitcnt vmcnt(11)
	v_pk_fma_f32 v[60:61], v[60:61], v[170:171], v[216:217]
	v_pk_fma_f32 v[58:59], v[58:59], v[168:169], v[214:215]
	global_load_dwordx4 v[214:217], v235, s[0:1] offset:576
	s_waitcnt vmcnt(11)
	v_pk_fma_f32 v[56:57], v[56:57], v[170:171], v[220:221]
	v_pk_fma_f32 v[54:55], v[54:55], v[168:169], v[218:219]
	global_load_dwordx4 v[218:221], v210, s[0:1] offset:576
	s_waitcnt vmcnt(11)
	v_pk_fma_f32 v[52:53], v[52:53], v[170:171], v[224:225]
	v_pk_fma_f32 v[50:51], v[50:51], v[168:169], v[222:223]
	global_load_dwordx4 v[222:225], v211, s[0:1] offset:576
	s_waitcnt vmcnt(11)
	v_pk_fma_f32 v[48:49], v[48:49], v[170:171], v[228:229]
	v_pk_fma_f32 v[46:47], v[46:47], v[168:169], v[226:227]
	s_waitcnt vmcnt(10)
	v_pk_fma_f32 v[44:45], v[44:45], v[170:171], v[232:233]
	v_pk_fma_f32 v[42:43], v[42:43], v[168:169], v[230:231]
	s_waitcnt vmcnt(9)
	v_pk_fma_f32 v[36:37], v[36:37], v[170:171], v[242:243]
	v_pk_fma_f32 v[34:35], v[34:35], v[168:169], v[240:241]
	s_waitcnt vmcnt(8)
	v_pk_fma_f32 v[32:33], v[32:33], v[170:171], v[246:247]
	v_pk_fma_f32 v[30:31], v[30:31], v[168:169], v[244:245]
	s_waitcnt vmcnt(7)
	v_pk_fma_f32 v[40:41], v[40:41], v[174:175], v[178:179]
	v_pk_fma_f32 v[38:39], v[38:39], v[172:173], v[176:177]
	s_waitcnt vmcnt(6)
	v_pk_fma_f32 v[28:29], v[28:29], v[174:175], v[182:183]
	v_pk_fma_f32 v[26:27], v[26:27], v[172:173], v[180:181]
	s_waitcnt vmcnt(5)
	v_pk_fma_f32 v[24:25], v[24:25], v[174:175], v[186:187]
	v_pk_fma_f32 v[22:23], v[22:23], v[172:173], v[184:185]
	s_waitcnt vmcnt(4)
	v_pk_fma_f32 v[20:21], v[20:21], v[174:175], v[190:191]
	v_pk_fma_f32 v[18:19], v[18:19], v[172:173], v[188:189]
	s_waitcnt vmcnt(3)
	v_pk_fma_f32 v[16:17], v[16:17], v[174:175], v[194:195]
	v_pk_fma_f32 v[14:15], v[14:15], v[172:173], v[192:193]
	s_waitcnt vmcnt(2)
	v_pk_fma_f32 v[12:13], v[12:13], v[174:175], v[216:217]
	v_pk_fma_f32 v[10:11], v[10:11], v[172:173], v[214:215]
	s_waitcnt vmcnt(1)
	v_pk_fma_f32 v[8:9], v[8:9], v[174:175], v[220:221]
	v_pk_fma_f32 v[6:7], v[6:7], v[172:173], v[218:219]
	s_waitcnt vmcnt(0)
	v_pk_fma_f32 v[4:5], v[4:5], v[174:175], v[224:225]
	v_pk_fma_f32 v[2:3], v[2:3], v[172:173], v[222:223]
	global_store_dwordx4 v159, v[126:129], s[0:1] sc1
	global_store_dwordx4 v153, v[122:125], s[0:1] sc1
	global_store_dwordx4 v196, v[118:121], s[0:1] sc1
	global_store_dwordx4 v197, v[114:117], s[0:1] sc1
	global_store_dwordx4 v234, v[110:113], s[0:1] sc1
	global_store_dwordx4 v235, v[106:109], s[0:1] sc1
	global_store_dwordx4 v210, v[98:101], s[0:1] sc1
	global_store_dwordx4 v211, v[94:97], s[0:1] sc1
	global_store_dwordx4 v159, v[102:105], s[0:1] offset:64 sc1
	global_store_dwordx4 v153, v[90:93], s[0:1] offset:64 sc1
	global_store_dwordx4 v196, v[86:89], s[0:1] offset:64 sc1
	global_store_dwordx4 v197, v[82:85], s[0:1] offset:64 sc1
	global_store_dwordx4 v234, v[78:81], s[0:1] offset:64 sc1
	global_store_dwordx4 v235, v[74:77], s[0:1] offset:64 sc1
	global_store_dwordx4 v210, v[70:73], s[0:1] offset:64 sc1
	global_store_dwordx4 v211, v[66:69], s[0:1] offset:64 sc1
	global_store_dwordx4 v159, v[62:65], s[0:1] offset:512 sc1
	global_store_dwordx4 v153, v[58:61], s[0:1] offset:512 sc1
	global_store_dwordx4 v196, v[54:57], s[0:1] offset:512 sc1
	global_store_dwordx4 v197, v[50:53], s[0:1] offset:512 sc1
	global_store_dwordx4 v234, v[46:49], s[0:1] offset:512 sc1
	global_store_dwordx4 v235, v[42:45], s[0:1] offset:512 sc1
	global_store_dwordx4 v210, v[34:37], s[0:1] offset:512 sc1
	global_store_dwordx4 v211, v[30:33], s[0:1] offset:512 sc1
	global_store_dwordx4 v159, v[38:41], s[0:1] offset:576 sc1
	global_store_dwordx4 v153, v[26:29], s[0:1] offset:576 sc1
	global_store_dwordx4 v196, v[22:25], s[0:1] offset:576 sc1
	global_store_dwordx4 v197, v[18:21], s[0:1] offset:576 sc1
	global_store_dwordx4 v234, v[14:17], s[0:1] offset:576 sc1
	global_store_dwordx4 v235, v[10:13], s[0:1] offset:576 sc1
	global_store_dwordx4 v210, v[6:9], s[0:1] offset:576 sc1
	global_store_dwordx4 v211, v[2:5], s[0:1] offset:576 sc1
	s_cbranch_vccnz .LBB0_1014
	s_andn2_b64 vcc, exec, s[40:41]
	s_cbranch_vccnz .LBB0_1013
	s_barrier
	s_branch .LBB0_1013

.LBB0_1250:
	s_sub_i32 s0, s37, 64
	s_ashr_i32 s1, s37, 31
	s_cmp_lt_i32 s37, 64
	s_cselect_b32 s1, s1, 0
	s_cselect_b32 s0, s37, s0
	s_movk_i32 s8, 0x4800
	s_cselect_b32 s2, s79, s97
	s_cselect_b32 s3, s78, s96
	s_cselect_b32 s8, 0x2400, s8
	s_lshl_b64 s[0:1], s[0:1], 20
	s_add_u32 s0, s3, s0
	s_addc_u32 s1, s2, s1
	s_cmp_gt_i32 s37, 31
	s_cselect_b32 s2, s8, 0
	s_lshl_b32 s2, s2, 2
	v_lshl_or_b32 v152, s36, 8, v157
	s_add_u32 s2, s29, s2
	v_ashrrev_i32_e32 v153, 31, v152
	s_addc_u32 s3, s30, 0
	v_lshlrev_b64 v[152:153], 2, v[152:153]
	global_load_dwordx4 v[160:163], v152, s[2:3]
	global_load_dwordx4 v[164:167], v152, s[2:3] offset:64
	global_load_dwordx4 v[168:171], v152, s[2:3] offset:512
	global_load_dwordx4 v[172:175], v152, s[2:3] offset:576
	v_add_u32_e32 v159, v152, v132
	v_add_u32_e32 v153, v152, v136
	v_add_u32_e32 v196, v152, v138
	v_add_u32_e32 v197, v152, v140
	v_add_u32_e32 v234, v152, v134
	v_add_u32_e32 v235, v152, v142
	v_add_u32_e32 v210, v152, v144
	v_add_u32_e32 v211, v152, v146
	global_load_dwordx4 v[176:179], v159, s[0:1]
	global_load_dwordx4 v[180:183], v153, s[0:1]
	global_load_dwordx4 v[184:187], v196, s[0:1]
	global_load_dwordx4 v[188:191], v197, s[0:1]
	global_load_dwordx4 v[192:195], v234, s[0:1]
	global_load_dwordx4 v[214:217], v235, s[0:1]
	global_load_dwordx4 v[218:221], v210, s[0:1]
	global_load_dwordx4 v[222:225], v211, s[0:1]
	global_load_dwordx4 v[226:229], v159, s[0:1] offset:64
	global_load_dwordx4 v[230:233], v153, s[0:1] offset:64
	global_load_dwordx4 v[240:243], v196, s[0:1] offset:64
	global_load_dwordx4 v[244:247], v197, s[0:1] offset:64
	v_readlane_b32 s18, v249, 56
	s_mov_b64 s[2:3], -1
	s_and_b64 vcc, exec, s[38:39]
	v_readlane_b32 s19, v249, 57
	s_waitcnt vmcnt(11)
	v_pk_mul_f32 v[160:161], v[160:161], 0.5 op_sel_hi:[1,0]
	v_pk_mul_f32 v[162:163], v[162:163], 0.5 op_sel_hi:[1,0]
	v_pk_fma_f32 v[128:129], v[128:129], v[162:163], v[178:179]
	v_pk_fma_f32 v[126:127], v[126:127], v[160:161], v[176:177]
	global_load_dwordx4 v[176:179], v234, s[0:1] offset:64
	s_waitcnt vmcnt(11)
	v_pk_fma_f32 v[124:125], v[124:125], v[162:163], v[182:183]
	v_pk_fma_f32 v[122:123], v[122:123], v[160:161], v[180:181]
	global_load_dwordx4 v[180:183], v235, s[0:1] offset:64
	s_waitcnt vmcnt(11)
	v_pk_fma_f32 v[120:121], v[120:121], v[162:163], v[186:187]
	v_pk_fma_f32 v[118:119], v[118:119], v[160:161], v[184:185]
	global_load_dwordx4 v[184:187], v210, s[0:1] offset:64
	s_waitcnt vmcnt(11)
	v_pk_fma_f32 v[116:117], v[116:117], v[162:163], v[190:191]
	v_pk_fma_f32 v[114:115], v[114:115], v[160:161], v[188:189]
	global_load_dwordx4 v[188:191], v211, s[0:1] offset:64
	s_waitcnt vmcnt(11)
	v_pk_fma_f32 v[112:113], v[112:113], v[162:163], v[194:195]
	v_pk_fma_f32 v[110:111], v[110:111], v[160:161], v[192:193]
	global_load_dwordx4 v[192:195], v159, s[0:1] offset:512
	s_waitcnt vmcnt(11)
	v_pk_fma_f32 v[108:109], v[108:109], v[162:163], v[216:217]
	v_pk_fma_f32 v[106:107], v[106:107], v[160:161], v[214:215]
	global_load_dwordx4 v[214:217], v153, s[0:1] offset:512
	s_waitcnt vmcnt(11)
	v_pk_fma_f32 v[104:105], v[104:105], v[162:163], v[220:221]
	v_pk_fma_f32 v[102:103], v[102:103], v[160:161], v[218:219]
	global_load_dwordx4 v[218:221], v196, s[0:1] offset:512
	s_waitcnt vmcnt(11)
	v_pk_fma_f32 v[96:97], v[96:97], v[162:163], v[224:225]
	v_pk_fma_f32 v[94:95], v[94:95], v[160:161], v[222:223]
	global_load_dwordx4 v[222:225], v197, s[0:1] offset:512
	s_waitcnt vmcnt(11)
	v_pk_mul_f32 v[164:165], v[164:165], 0.5 op_sel_hi:[1,0]
	v_pk_mul_f32 v[166:167], v[166:167], 0.5 op_sel_hi:[1,0]
	v_pk_fma_f32 v[100:101], v[100:101], v[166:167], v[228:229]
	v_pk_fma_f32 v[98:99], v[98:99], v[164:165], v[226:227]
	global_load_dwordx4 v[226:229], v234, s[0:1] offset:512
	s_waitcnt vmcnt(11)
	v_pk_fma_f32 v[92:93], v[92:93], v[166:167], v[232:233]
	v_pk_fma_f32 v[90:91], v[90:91], v[164:165], v[230:231]
	global_load_dwordx4 v[230:233], v235, s[0:1] offset:512
	s_waitcnt vmcnt(11)
	v_pk_fma_f32 v[88:89], v[88:89], v[166:167], v[242:243]
	v_pk_fma_f32 v[86:87], v[86:87], v[164:165], v[240:241]
	global_load_dwordx4 v[240:243], v210, s[0:1] offset:512
	s_waitcnt vmcnt(11)
	v_pk_fma_f32 v[84:85], v[84:85], v[166:167], v[246:247]
	v_pk_fma_f32 v[82:83], v[82:83], v[164:165], v[244:245]
	global_load_dwordx4 v[244:247], v211, s[0:1] offset:512
	s_waitcnt vmcnt(11)
	v_pk_fma_f32 v[80:81], v[80:81], v[166:167], v[178:179]
	v_pk_fma_f32 v[78:79], v[78:79], v[164:165], v[176:177]
	global_load_dwordx4 v[176:179], v159, s[0:1] offset:576
	s_waitcnt vmcnt(11)
	v_pk_fma_f32 v[76:77], v[76:77], v[166:167], v[182:183]
	v_pk_fma_f32 v[74:75], v[74:75], v[164:165], v[180:181]
	global_load_dwordx4 v[180:183], v153, s[0:1] offset:576
	s_waitcnt vmcnt(11)
	v_pk_fma_f32 v[72:73], v[72:73], v[166:167], v[186:187]
	v_pk_fma_f32 v[70:71], v[70:71], v[164:165], v[184:185]
	global_load_dwordx4 v[184:187], v196, s[0:1] offset:576
	s_waitcnt vmcnt(11)
	v_pk_fma_f32 v[64:65], v[64:65], v[166:167], v[190:191]
	v_pk_fma_f32 v[62:63], v[62:63], v[164:165], v[188:189]
	global_load_dwordx4 v[188:191], v197, s[0:1] offset:576
	s_waitcnt vmcnt(11)
	v_pk_mul_f32 v[168:169], v[168:169], 0.5 op_sel_hi:[1,0]
	v_pk_mul_f32 v[170:171], v[170:171], 0.5 op_sel_hi:[1,0]
	v_pk_fma_f32 v[68:69], v[68:69], v[170:171], v[194:195]
	v_pk_fma_f32 v[66:67], v[66:67], v[168:169], v[192:193]
	global_load_dwordx4 v[192:195], v234, s[0:1] offset:576
	s_waitcnt vmcnt(11)
	v_pk_fma_f32 v[60:61], v[60:61], v[170:171], v[216:217]
	v_pk_fma_f32 v[58:59], v[58:59], v[168:169], v[214:215]
	global_load_dwordx4 v[214:217], v235, s[0:1] offset:576
	s_waitcnt vmcnt(11)
	v_pk_fma_f32 v[56:57], v[56:57], v[170:171], v[220:221]
	v_pk_fma_f32 v[54:55], v[54:55], v[168:169], v[218:219]
	global_load_dwordx4 v[218:221], v210, s[0:1] offset:576
	s_waitcnt vmcnt(11)
	v_pk_fma_f32 v[52:53], v[52:53], v[170:171], v[224:225]
	v_pk_fma_f32 v[50:51], v[50:51], v[168:169], v[222:223]
	global_load_dwordx4 v[222:225], v211, s[0:1] offset:576
	s_waitcnt vmcnt(11)
	v_pk_fma_f32 v[48:49], v[48:49], v[170:171], v[228:229]
	v_pk_fma_f32 v[46:47], v[46:47], v[168:169], v[226:227]
	s_waitcnt vmcnt(10)
	v_pk_fma_f32 v[44:45], v[44:45], v[170:171], v[232:233]
	v_pk_fma_f32 v[42:43], v[42:43], v[168:169], v[230:231]
	s_waitcnt vmcnt(9)
	v_pk_fma_f32 v[40:41], v[40:41], v[170:171], v[242:243]
	v_pk_fma_f32 v[38:39], v[38:39], v[168:169], v[240:241]
	s_waitcnt vmcnt(8)
	v_pk_fma_f32 v[32:33], v[32:33], v[170:171], v[246:247]
	v_pk_fma_f32 v[30:31], v[30:31], v[168:169], v[244:245]
	s_waitcnt vmcnt(7)
	v_pk_mul_f32 v[172:173], v[172:173], 0.5 op_sel_hi:[1,0]
	v_pk_mul_f32 v[174:175], v[174:175], 0.5 op_sel_hi:[1,0]
	v_pk_fma_f32 v[36:37], v[36:37], v[174:175], v[178:179]
	v_pk_fma_f32 v[34:35], v[34:35], v[172:173], v[176:177]
	s_waitcnt vmcnt(6)
	v_pk_fma_f32 v[28:29], v[28:29], v[174:175], v[182:183]
	v_pk_fma_f32 v[26:27], v[26:27], v[172:173], v[180:181]
	s_waitcnt vmcnt(5)
	v_pk_fma_f32 v[24:25], v[24:25], v[174:175], v[186:187]
	v_pk_fma_f32 v[22:23], v[22:23], v[172:173], v[184:185]
	s_waitcnt vmcnt(4)
	v_pk_fma_f32 v[20:21], v[20:21], v[174:175], v[190:191]
	v_pk_fma_f32 v[18:19], v[18:19], v[172:173], v[188:189]
	s_waitcnt vmcnt(3)
	v_pk_fma_f32 v[16:17], v[16:17], v[174:175], v[194:195]
	v_pk_fma_f32 v[14:15], v[14:15], v[172:173], v[192:193]
	s_waitcnt vmcnt(2)
	v_pk_fma_f32 v[12:13], v[12:13], v[174:175], v[216:217]
	v_pk_fma_f32 v[10:11], v[10:11], v[172:173], v[214:215]
	s_waitcnt vmcnt(1)
	v_pk_fma_f32 v[8:9], v[8:9], v[174:175], v[220:221]
	v_pk_fma_f32 v[6:7], v[6:7], v[172:173], v[218:219]
	s_waitcnt vmcnt(0)
	v_pk_fma_f32 v[4:5], v[4:5], v[174:175], v[224:225]
	v_pk_fma_f32 v[2:3], v[2:3], v[172:173], v[222:223]
	global_store_dwordx4 v159, v[126:129], s[0:1] sc1
	global_store_dwordx4 v153, v[122:125], s[0:1] sc1
	global_store_dwordx4 v196, v[118:121], s[0:1] sc1
	global_store_dwordx4 v197, v[114:117], s[0:1] sc1
	global_store_dwordx4 v234, v[110:113], s[0:1] sc1
	global_store_dwordx4 v235, v[106:109], s[0:1] sc1
	global_store_dwordx4 v210, v[102:105], s[0:1] sc1
	global_store_dwordx4 v211, v[94:97], s[0:1] sc1
	global_store_dwordx4 v159, v[98:101], s[0:1] offset:64 sc1
	global_store_dwordx4 v153, v[90:93], s[0:1] offset:64 sc1
	global_store_dwordx4 v196, v[86:89], s[0:1] offset:64 sc1
	global_store_dwordx4 v197, v[82:85], s[0:1] offset:64 sc1
	global_store_dwordx4 v234, v[78:81], s[0:1] offset:64 sc1
	global_store_dwordx4 v235, v[74:77], s[0:1] offset:64 sc1
	global_store_dwordx4 v210, v[70:73], s[0:1] offset:64 sc1
	global_store_dwordx4 v211, v[62:65], s[0:1] offset:64 sc1
	global_store_dwordx4 v159, v[66:69], s[0:1] offset:512 sc1
	global_store_dwordx4 v153, v[58:61], s[0:1] offset:512 sc1
	global_store_dwordx4 v196, v[54:57], s[0:1] offset:512 sc1
	global_store_dwordx4 v197, v[50:53], s[0:1] offset:512 sc1
	global_store_dwordx4 v234, v[46:49], s[0:1] offset:512 sc1
	global_store_dwordx4 v235, v[42:45], s[0:1] offset:512 sc1
	global_store_dwordx4 v210, v[38:41], s[0:1] offset:512 sc1
	global_store_dwordx4 v211, v[30:33], s[0:1] offset:512 sc1
	global_store_dwordx4 v159, v[34:37], s[0:1] offset:576 sc1
	global_store_dwordx4 v153, v[26:29], s[0:1] offset:576 sc1
	global_store_dwordx4 v196, v[22:25], s[0:1] offset:576 sc1
	global_store_dwordx4 v197, v[18:21], s[0:1] offset:576 sc1
	global_store_dwordx4 v234, v[14:17], s[0:1] offset:576 sc1
	global_store_dwordx4 v235, v[10:13], s[0:1] offset:576 sc1
	global_store_dwordx4 v210, v[6:9], s[0:1] offset:576 sc1
	global_store_dwordx4 v211, v[2:5], s[0:1] offset:576 sc1
	s_cbranch_vccnz .LBB0_1235
	s_andn2_b64 vcc, exec, s[42:43]
	s_cbranch_vccnz .LBB0_1234
	s_barrier
	s_branch .LBB0_1234
